# P7 epilogue: six pass-1 conv-weight loads hoisted from behind the halo barrier to the epilogue head
# speedup vs baseline: 1.0103x; 1.0081x over previous
.LBB0_688:
	s_mul_hi_i32 s0, s20, 0x3e0f83e1
	s_lshr_b32 s1, s0, 31
	s_ashr_i32 s0, s0, 3
	s_add_i32 s0, s0, s1
	s_mul_i32 s1, s0, 33
	s_sub_i32 s16, s20, s1
	s_mul_i32 s1, s16, 0xfe
	s_lshl_b32 s0, s0, 13
	s_min_i32 s41, s1, 0x1f00
	s_add_i32 s41, s41, s0
	v_add_u32_e32 v194, s41, v200
	v_lshl_or_b32 v192, s12, 7, v211
	s_add_u32 s98, s82, 0x2c00
	s_addc_u32 s99, s83, 0
	s_add_u32 s100, s82, 0x8400
	s_addc_u32 s101, s83, 0
	v_lshlrev_b32_e32 v222, 2, v192
	v_ashrrev_i32_e32 v193, 31, v192
	global_load_dwordx4 v[120:123], v222, s[82:83]
	global_load_dwordx4 v[124:127], v222, s[98:99]
	global_load_dwordx4 v[128:131], v222, s[100:101]
	s_add_u32 s98, s82, 0xdc00
	s_addc_u32 s99, s83, 0
	global_load_dwordx4 v[132:135], v222, s[98:99]
	v_lshl_add_u64 v[196:197], v[192:193], 2, s[82:83]
	s_waitcnt vmcnt(10)
	v_mov_b32_e32 v44, v236
	v_mov_b32_e32 v45, v237
	v_mov_b32_e32 v46, v238
	v_mov_b32_e32 v47, v239
	v_mov_b32_e32 v140, v240
	v_mov_b32_e32 v141, v241
	v_mov_b32_e32 v142, v242
	v_mov_b32_e32 v143, v243
	v_mov_b32_e32 v40, v246
	v_mov_b32_e32 v41, v247
	v_mov_b32_e32 v42, v248
	v_mov_b32_e32 v43, v249
	v_mov_b32_e32 v136, v250
	v_mov_b32_e32 v137, v251
	v_mov_b32_e32 v138, v252
	v_mov_b32_e32 v139, v253
	v_mov_b32_e32 v198, v208
	v_mov_b32_e32 v221, v203
	v_mov_b32_e32 v220, v204
	v_mov_b32_e32 v219, v205
	v_mov_b32_e32 v218, v206
	v_mov_b32_e32 v199, v207
	v_fmamk_f32 v168, v244, 0x3a800000, v215
	v_rsq_f32_e32 v168, v168
	v_fmamk_f32 v169, v245, 0x3a800000, v215
	v_rsq_f32_e32 v170, v169
	v_pk_fma_f32 v[162:163], v[118:119], v[168:169], v[142:143] op_sel_hi:[1,0,1]
	v_pk_fma_f32 v[160:161], v[116:117], v[168:169], v[140:141] op_sel_hi:[1,0,1]
	v_pk_fma_f32 v[66:67], v[66:67], v[168:169], v[46:47] op_sel_hi:[1,0,1]
	v_pk_fma_f32 v[64:65], v[64:65], v[168:169], v[44:45] op_sel_hi:[1,0,1]
	v_pk_fma_f32 v[166:167], v[114:115], v[168:169], v[138:139] op_sel_hi:[1,0,1]
	v_pk_fma_f32 v[164:165], v[112:113], v[168:169], v[136:137] op_sel_hi:[1,0,1]
	s_add_u32 s98, s82, 0x5800
	s_addc_u32 s99, s83, 0
	s_add_u32 s100, s82, 0xb000
	s_addc_u32 s101, s83, 0
	global_load_dwordx4 v[112:115], v222, s[98:99]
	global_load_dwordx4 v[116:119], v222, s[100:101]
	v_pk_fma_f32 v[70:71], v[70:71], v[168:169], v[42:43] op_sel_hi:[1,0,1]
	v_pk_fma_f32 v[68:69], v[68:69], v[168:169], v[40:41] op_sel_hi:[1,0,1]
	v_pk_fma_f32 v[98:99], v[98:99], v[170:171], v[142:143] op_sel_hi:[1,0,1]
	v_pk_fma_f32 v[96:97], v[96:97], v[170:171], v[140:141] op_sel_hi:[1,0,1]
	v_pk_fma_f32 v[26:27], v[26:27], v[170:171], v[46:47] op_sel_hi:[1,0,1]
	v_pk_fma_f32 v[24:25], v[24:25], v[170:171], v[44:45] op_sel_hi:[1,0,1]
	v_pk_fma_f32 v[106:107], v[106:107], v[170:171], v[138:139] op_sel_hi:[1,0,1]
	v_pk_fma_f32 v[104:105], v[104:105], v[170:171], v[136:137] op_sel_hi:[1,0,1]
	v_pk_fma_f32 v[38:39], v[38:39], v[170:171], v[42:43] op_sel_hi:[1,0,1]
	v_pk_fma_f32 v[36:37], v[36:37], v[170:171], v[40:41] op_sel_hi:[1,0,1]
	s_and_saveexec_b64 s[0:1], s[4:5]
	s_cbranch_execz .LBB0_690
	ds_write_b128 v216, v[160:163]
	ds_write_b128 v216, v[64:67] offset:16
	ds_write_b128 v216, v[164:167] offset:32
	ds_write_b128 v216, v[68:71] offset:48
	ds_write_b128 v217, v[96:99]
	ds_write_b128 v217, v[24:27] offset:16
	ds_write_b128 v217, v[104:107] offset:32
	ds_write_b128 v217, v[36:39] offset:48
.LBB0_690:
	s_or_b64 exec, exec, s[0:1]
	s_waitcnt lgkmcnt(0)
	s_barrier
	v_cndmask_b32_e64 v168, 0, 1, s[34:35]
	v_mov_b32_e32 v232, 0
	v_add_u32_e32 v195, s63, v202
	v_cmp_ne_u32_e64 s[12:13], 1, v168
	s_andn2_b64 vcc, exec, s[34:35]
	v_mov_b32_e32 v235, 0
	v_mov_b32_e32 v238, 0
	v_mov_b32_e32 v241, 0
	v_mov_b32_e32 v242, 0
	v_mov_b32_e32 v243, 0
	v_mov_b32_e32 v244, 0
	v_mov_b32_e32 v245, 0
	v_mov_b32_e32 v168, 0
	v_mov_b32_e32 v169, 0
	v_mov_b32_e32 v170, 0
	v_mov_b32_e32 v171, 0
	v_mov_b32_e32 v172, 0
	v_mov_b32_e32 v173, 0
	v_mov_b32_e32 v174, 0
	v_mov_b32_e32 v175, 0
	s_cbranch_vccnz .LBB0_692
	ds_read_b128 v[168:171], v195 offset:256
	ds_read_b128 v[222:225], v195
	ds_read_b128 v[226:229], v195 offset:32
	ds_read_b128 v[172:175], v195 offset:288
	s_waitcnt lgkmcnt(2)
	v_cndmask_b32_e64 v232, v168, v222, s[6:7]
	v_cndmask_b32_e64 v235, v169, v223, s[6:7]
	v_cndmask_b32_e64 v238, v170, v224, s[6:7]
	v_cndmask_b32_e64 v241, v171, v225, s[6:7]
	s_waitcnt lgkmcnt(0)
	v_cndmask_b32_e64 v242, v172, v226, s[6:7]
	v_cndmask_b32_e64 v243, v173, v227, s[6:7]
	v_cndmask_b32_e64 v244, v174, v228, s[6:7]
	v_cndmask_b32_e64 v245, v175, v229, s[6:7]
.LBB0_692:
	s_waitcnt vmcnt(0)
	v_fmamk_f32 v198, v198, 0x3a800000, v215
	v_rsq_f32_e32 v198, v198
	s_cmp_lt_i32 s16, 32
	s_cselect_b32 s0, 2, 0xc2
	s_cmp_lg_u32 s16, 0
	v_pk_fma_f32 v[158:159], v[158:159], v[198:199], v[142:143] op_sel_hi:[1,0,1]
	v_pk_fma_f32 v[156:157], v[156:157], v[198:199], v[140:141] op_sel_hi:[1,0,1]
	v_pk_fma_f32 v[154:155], v[154:155], v[198:199], v[138:139] op_sel_hi:[1,0,1]
	v_pk_fma_f32 v[152:153], v[152:153], v[198:199], v[136:137] op_sel_hi:[1,0,1]
	s_cselect_b32 s46, s0, 0
	s_nop 1
	v_mov_b32_dpp v222, v156 row_ror:1 row_mask:0xf bank_mask:0xf
	v_mov_b32_dpp v226, v156 row_ror:2 row_mask:0xf bank_mask:0xf
	v_mov_b32_dpp v223, v157 row_ror:1 row_mask:0xf bank_mask:0xf
	v_mov_b32_dpp v227, v157 row_ror:2 row_mask:0xf bank_mask:0xf
	v_mov_b32_dpp v224, v158 row_ror:1 row_mask:0xf bank_mask:0xf
	v_mov_b32_dpp v228, v158 row_ror:2 row_mask:0xf bank_mask:0xf
	v_mov_b32_dpp v225, v159 row_ror:1 row_mask:0xf bank_mask:0xf
	v_mov_b32_dpp v229, v159 row_ror:2 row_mask:0xf bank_mask:0xf
	v_mov_b32_dpp v230, v152 row_ror:1 row_mask:0xf bank_mask:0xf
	v_mov_b32_dpp v233, v152 row_ror:2 row_mask:0xf bank_mask:0xf
	v_mov_b32_dpp v231, v153 row_ror:1 row_mask:0xf bank_mask:0xf
	v_mov_b32_dpp v236, v153 row_ror:2 row_mask:0xf bank_mask:0xf
	v_mov_b32_dpp v234, v154 row_ror:1 row_mask:0xf bank_mask:0xf
	v_mov_b32_dpp v239, v154 row_ror:2 row_mask:0xf bank_mask:0xf
	v_mov_b32_dpp v237, v155 row_ror:1 row_mask:0xf bank_mask:0xf
	v_mov_b32_dpp v240, v155 row_ror:2 row_mask:0xf bank_mask:0xf
	v_cmp_le_u32_e64 s[0:1], s46, v200
	s_and_saveexec_b64 s[16:17], s[0:1]
	s_cbranch_execz .LBB0_694
	v_cndmask_b32_e64 v244, v244, v239, s[8:9]
	v_cndmask_b32_e64 v245, v245, v240, s[8:9]
	v_cndmask_b32_e64 v174, v234, v174, s[6:7]
	v_cndmask_b32_e64 v175, v237, v175, s[6:7]
	s_waitcnt vmcnt(4)
	v_pk_mul_f32 v[244:245], v[126:127], v[244:245]
	v_cndmask_b32_e64 v170, v224, v170, s[6:7]
	s_waitcnt vmcnt(2)
	v_pk_fma_f32 v[174:175], v[130:131], v[174:175], v[244:245]
	v_cndmask_b32_e64 v171, v225, v171, s[6:7]
	s_waitcnt vmcnt(0)
	v_pk_fma_f32 v[154:155], v[154:155], v[134:135], v[174:175]
	v_cndmask_b32_e64 v174, v238, v228, s[8:9]
	v_cndmask_b32_e64 v175, v241, v229, s[8:9]
	v_pk_mul_f32 v[174:175], v[122:123], v[174:175]
	v_cndmask_b32_e64 v242, v242, v233, s[8:9]
	v_pk_fma_f32 v[170:171], v[114:115], v[170:171], v[174:175]
	v_cndmask_b32_e64 v243, v243, v236, s[8:9]
	v_pk_fma_f32 v[158:159], v[158:159], v[118:119], v[170:171]
	v_cndmask_b32_e64 v172, v230, v172, s[6:7]
	v_mul_f32_e32 v170, 0xbfb8aa3b, v159
	v_exp_f32_e32 v170, v170
	v_cndmask_b32_e64 v173, v231, v173, s[6:7]
	v_pk_mul_f32 v[242:243], v[124:125], v[242:243]
	v_mul_f32_e32 v171, 0xbfb8aa3b, v158
	v_add_f32_e32 v170, 1.0, v170
	v_pk_fma_f32 v[172:173], v[128:129], v[172:173], v[242:243]
	v_rcp_f32_e32 v170, v170
	v_pk_fma_f32 v[152:153], v[152:153], v[132:133], v[172:173]
	v_cndmask_b32_e64 v172, v232, v226, s[8:9]
	v_cndmask_b32_e64 v173, v235, v227, s[8:9]
	v_exp_f32_e32 v171, v171
	v_pk_mul_f32 v[172:173], v[120:121], v[172:173]
	v_cndmask_b32_e64 v168, v222, v168, s[6:7]
	v_cndmask_b32_e64 v169, v223, v169, s[6:7]
	v_pk_fma_f32 v[168:169], v[112:113], v[168:169], v[172:173]
	v_mul_f32_e32 v159, v159, v170
	v_pk_fma_f32 v[156:157], v[156:157], v[116:117], v[168:169]
	v_mul_f32_e32 v155, v159, v155
	v_add_f32_e32 v159, 1.0, v171
	v_mul_f32_e32 v168, 0xbfb8aa3b, v157
	v_mul_f32_e32 v169, 0xbfb8aa3b, v156
	v_rcp_f32_e32 v159, v159
	v_exp_f32_e32 v168, v168
	v_exp_f32_e32 v169, v169
	v_mul_f32_e32 v158, v158, v159
	v_add_f32_e32 v159, 1.0, v168
	v_add_f32_e32 v168, 1.0, v169
	v_rcp_f32_e32 v159, v159
	v_rcp_f32_e32 v168, v168
	v_mul_f32_e32 v154, v158, v154
	v_mul_f32_e32 v157, v157, v159
	v_mul_f32_e32 v156, v156, v168
	v_mul_f32_e32 v153, v157, v153
	v_mul_f32_e32 v152, v156, v152
	v_cvt_pk_bf16_f32 v152, v152, v153
	v_cvt_pk_bf16_f32 v153, v154, v155
	v_mov_b64_e32 v[154:155], s[30:31]
	v_mad_i64_i32 v[154:155], s[18:19], v194, s67, v[154:155]
	v_lshl_add_u64 v[154:155], v[192:193], 1, v[154:155]
	global_store_dwordx2 v[154:155], v[152:153], off
